# prologue de-serialisation: attention K/V staging issues all 8 loads up front with counted vmcnt waits (was 4 serial round trips)
# speedup vs baseline: 1.0040x; 1.0040x over previous
.LBB0_440:
	s_or_b64 exec, exec, s[0:1]
	s_mov_b32 s0, s55
	s_waitcnt lgkmcnt(0)
	s_barrier
	v_mbcnt_lo_u32_b32 v122, -1, 0
	v_mbcnt_hi_u32_b32 v122, -1, v122
	s_waitcnt vmcnt(22)
	s_waitcnt vmcnt(8)
	v_lshl_add_u32 v111, s0, 6, v122
	v_and_b32_e32 v4, 7, v122
	v_readlane_b32 s0, v255, 6
	v_lshlrev_b32_e32 v0, 4, v4
	v_readlane_b32 s1, v255, 7
	v_readfirstlane_b32 s20, v111
	v_readlane_b32 s6, v255, 4
	v_add_u32_e32 v123, 0x200, v111
	v_lshl_add_u64 v[18:19], s[0:1], 0, v[0:1]
	s_xor_b64 s[0:1], s[84:85], -1
	s_movk_i32 s7, 0x3400
	v_add_u32_e32 v124, 0x400, v111
	v_add_u32_e32 v125, 0x600, v111
	v_ashrrev_i32_e32 v3, 3, v111
	v_ashrrev_i32_e32 v20, 3, v123
	v_ashrrev_i32_e32 v21, 3, v124
	v_ashrrev_i32_e32 v22, 3, v125
	v_mov_b32_e32 v70, 0
	v_mov_b32_e32 v71, 0
	v_mov_b32_e32 v72, 0
	v_mov_b32_e32 v73, 0
	v_mov_b32_e32 v74, 0
	v_mov_b32_e32 v75, 0
	v_mov_b32_e32 v76, 0
	v_mov_b32_e32 v77, 0
	v_mov_b32_e32 v78, 0
	v_mov_b32_e32 v79, 0
	v_mov_b32_e32 v80, 0
	v_mov_b32_e32 v81, 0
	v_mov_b32_e32 v82, 0
	v_mov_b32_e32 v83, 0
	v_mov_b32_e32 v84, 0
	v_mov_b32_e32 v85, 0
	v_mov_b32_e32 v86, 0
	v_mov_b32_e32 v87, 0
	v_mov_b32_e32 v88, 0
	v_mov_b32_e32 v89, 0
	v_mov_b32_e32 v90, 0
	v_mov_b32_e32 v91, 0
	v_mov_b32_e32 v92, 0
	v_mov_b32_e32 v93, 0
	v_mov_b32_e32 v94, 0
	v_mov_b32_e32 v95, 0
	v_mov_b32_e32 v96, 0
	v_mov_b32_e32 v97, 0
	v_mov_b32_e32 v222, 0
	v_mov_b32_e32 v223, 0
	v_mov_b32_e32 v224, 0
	v_mov_b32_e32 v225, 0
	v_cmp_lt_i32_e32 vcc, 0x7f, v3
	v_add_u32_e32 v0, s6, v3
	s_nop 1
	s_or_b64 s[4:5], vcc, s[0:1]
	s_and_saveexec_b64 s[2:3], s[4:5]
	s_cbranch_execz .Lattnst_skip0
	v_mad_i64_i32 v[8:9], s[4:5], v0, s7, v[18:19]
	v_add_co_u32_e32 v8, vcc, 0x1000, v8
	s_nop 1
	v_addc_co_u32_e32 v9, vcc, 0, v9, vcc
	global_load_dwordx4 v[70:73], v[8:9], off
	s_nop 0
	global_load_dwordx4 v[74:77], v[8:9], off offset:512
.Lattnst_skip0:
	s_or_b64 exec, exec, s[2:3]
	v_cmp_lt_i32_e32 vcc, 0x7f, v20
	v_add_u32_e32 v0, s6, v20
	s_nop 1
	s_or_b64 s[4:5], vcc, s[0:1]
	s_and_saveexec_b64 s[2:3], s[4:5]
	s_cbranch_execz .Lattnst_skip1
	v_mad_i64_i32 v[8:9], s[4:5], v0, s7, v[18:19]
	v_add_co_u32_e32 v8, vcc, 0x1000, v8
	s_nop 1
	v_addc_co_u32_e32 v9, vcc, 0, v9, vcc
	global_load_dwordx4 v[78:81], v[8:9], off
	s_nop 0
	global_load_dwordx4 v[82:85], v[8:9], off offset:512
.Lattnst_skip1:
	s_or_b64 exec, exec, s[2:3]
	v_cmp_lt_i32_e32 vcc, 0x7f, v21
	v_add_u32_e32 v0, s6, v21
	s_nop 1
	s_or_b64 s[4:5], vcc, s[0:1]
	s_and_saveexec_b64 s[2:3], s[4:5]
	s_cbranch_execz .Lattnst_skip2
	v_mad_i64_i32 v[8:9], s[4:5], v0, s7, v[18:19]
	v_add_co_u32_e32 v8, vcc, 0x1000, v8
	s_nop 1
	v_addc_co_u32_e32 v9, vcc, 0, v9, vcc
	global_load_dwordx4 v[86:89], v[8:9], off
	s_nop 0
	global_load_dwordx4 v[90:93], v[8:9], off offset:512
.Lattnst_skip2:
	s_or_b64 exec, exec, s[2:3]
	v_cmp_lt_i32_e32 vcc, 0x7f, v22
	v_add_u32_e32 v0, s6, v22
	s_nop 1
	s_or_b64 s[4:5], vcc, s[0:1]
	s_and_saveexec_b64 s[2:3], s[4:5]
	s_cbranch_execz .Lattnst_skip3
	v_mad_i64_i32 v[8:9], s[4:5], v0, s7, v[18:19]
	v_add_co_u32_e32 v8, vcc, 0x1000, v8
	s_nop 1
	v_addc_co_u32_e32 v9, vcc, 0, v9, vcc
	global_load_dwordx4 v[94:97], v[8:9], off
	s_nop 0
	global_load_dwordx4 v[222:225], v[8:9], off offset:512
.Lattnst_skip3:
	s_or_b64 exec, exec, s[2:3]
	v_lshl_add_u32 v16, v4, 4, 0
	s_movk_i32 s2, 0x1070
	v_mad_u32_u24 v17, v4, s2, v16
	v_mad_u32_u24 v5, v3, s52, v16
	v_lshl_add_u32 v0, v3, 1, v17
	s_waitcnt vmcnt(7)
	ds_write_b128 v5, v[70:73]
	s_waitcnt vmcnt(6)
	ds_write_b16 v0, v74 offset:36864
	ds_write_b16_d16_hi v0, v74 offset:37392
	ds_write_b16 v0, v75 offset:37920
	ds_write_b16_d16_hi v0, v75 offset:38448
	ds_write_b16 v0, v76 offset:38976
	ds_write_b16_d16_hi v0, v76 offset:39504
	ds_write_b16 v0, v77 offset:40032
	ds_write_b16_d16_hi v0, v77 offset:40560
	v_mad_u32_u24 v5, v20, s52, v16
	v_lshl_add_u32 v0, v20, 1, v17
	s_waitcnt vmcnt(5)
	ds_write_b128 v5, v[78:81]
	s_waitcnt vmcnt(4)
	ds_write_b16 v0, v82 offset:36864
	ds_write_b16_d16_hi v0, v82 offset:37392
	ds_write_b16 v0, v83 offset:37920
	ds_write_b16_d16_hi v0, v83 offset:38448
	ds_write_b16 v0, v84 offset:38976
	ds_write_b16_d16_hi v0, v84 offset:39504
	ds_write_b16 v0, v85 offset:40032
	ds_write_b16_d16_hi v0, v85 offset:40560
	v_mad_u32_u24 v5, v21, s52, v16
	v_lshl_add_u32 v0, v21, 1, v17
	s_waitcnt vmcnt(3)
	ds_write_b128 v5, v[86:89]
	s_waitcnt vmcnt(2)
	ds_write_b16 v0, v90 offset:36864
	ds_write_b16_d16_hi v0, v90 offset:37392
	ds_write_b16 v0, v91 offset:37920
	ds_write_b16_d16_hi v0, v91 offset:38448
	ds_write_b16 v0, v92 offset:38976
	ds_write_b16_d16_hi v0, v92 offset:39504
	ds_write_b16 v0, v93 offset:40032
	ds_write_b16_d16_hi v0, v93 offset:40560
	v_mad_u32_u24 v5, v22, s52, v16
	v_lshl_add_u32 v0, v22, 1, v17
	s_waitcnt vmcnt(1)
	ds_write_b128 v5, v[94:97]
	s_waitcnt vmcnt(0)
	ds_write_b16 v0, v222 offset:36864
	ds_write_b16_d16_hi v0, v222 offset:37392
	ds_write_b16 v0, v223 offset:37920
	ds_write_b16_d16_hi v0, v223 offset:38448
	ds_write_b16 v0, v224 offset:38976
	ds_write_b16_d16_hi v0, v224 offset:39504
	ds_write_b16 v0, v225 offset:40032
	ds_write_b16_d16_hi v0, v225 offset:40560
	s_mov_b32 s2, 0
	s_lshl_b32 s86, s78, 5
	v_readlane_b32 s36, v252, 12
	s_lshl_b64 s[0:1], s[86:87], 2
	v_readlane_b32 s50, v252, 26
	v_readlane_b32 s51, v252, 27
	s_nop 1
	s_add_u32 s12, s50, s0
	s_addc_u32 s13, s51, s1
	s_ashr_i32 s18, s20, 6
	v_readlane_b32 s0, v255, 8
	s_nop 1
	s_add_i32 s0, s0, s18
	s_ashr_i32 s1, s0, 31
	s_lshl_b64 s[4:5], s[0:1], 2
	v_and_b32_e32 v130, 31, v122
	s_add_u32 s4, s12, s4
	v_readlane_b32 s1, v255, 3
	s_addc_u32 s5, s13, s5
	s_nop 1
	v_or_b32_e32 v127, s1, v130
	s_lshl_b32 s0, s0, 6
	v_mul_u32_u24_e32 v2, 0x3400, v127
	v_mov_b32_e32 v3, v1
	s_ashr_i32 s1, s0, 31
	v_lshrrev_b32_e32 v0, 1, v122
	v_lshl_add_u64 v[2:3], s[68:69], 0, v[2:3]
	s_lshl_b64 s[6:7], s[0:1], 1
	v_and_b32_e32 v0, 16, v0
	v_lshl_add_u64 v[2:3], v[2:3], 0, s[6:7]
	v_lshl_add_u64 v[2:3], v[2:3], 0, v[0:1]
	s_waitcnt lgkmcnt(0)
	s_barrier
	global_load_dword v126, v1, s[4:5]
	global_load_dwordx4 v[82:85], v[2:3], off
	global_load_dwordx4 v[86:89], v[2:3], off offset:32
	global_load_dwordx4 v[90:93], v[2:3], off offset:64
	global_load_dwordx4 v[94:97], v[2:3], off offset:96
	v_and_b32_e32 v7, 64, v214
	v_xor_b32_e32 v6, 32, v214
	v_add_u32_e32 v7, 64, v7
	v_cmp_lt_i32_e64 s[4:5], v6, v7
	v_lshl_add_u64 v[4:5], s[68:69], 0, v[0:1]
	v_bfe_u32 v0, v122, 5, 1
	v_cndmask_b32_e64 v6, v214, v6, s[4:5]
	v_readlane_b32 s4, v253, 43
	v_lshlrev_b32_e32 v131, 4, v0
	v_lshlrev_b32_e32 v110, 2, v0
	v_lshlrev_b32_e32 v112, 3, v0
	v_mov_b32_e32 v113, v1
	v_readlane_b32 s5, v253, 44
	v_add_u32_e32 v128, 0, v131
	v_cmp_le_u32_e32 vcc, v110, v130
	v_cmp_lt_u32_e64 s[0:1], v110, v130
	v_lshlrev_b32_e32 v152, 2, v6
	v_and_or_b32 v132, v122, 63, 32
	v_lshl_add_u64 v[6:7], s[4:5], 0, v[112:113]
	s_mov_b64 s[4:5], 0xd0000
	v_sub_u32_e32 v129, v128, v112
	v_mul_u32_u24_e32 v133, 0x210, v130
	v_mul_u32_u24_e32 v134, 0x210, v132
	v_lshl_add_u64 v[114:115], v[4:5], 0, s[6:7]
	v_lshl_add_u64 v[116:117], v[6:7], 0, s[6:7]
	v_lshl_add_u64 v[118:119], v[2:3], 0, s[4:5]
	s_or_b64 s[4:5], vcc, s[84:85]
	s_or_b64 s[6:7], s[0:1], s[84:85]
	s_mov_b64 s[0:1], -1
	v_readlane_b32 s37, v252, 13
	v_readlane_b32 s38, v252, 14
	v_readlane_b32 s39, v252, 15
	v_readlane_b32 s40, v252, 16
	v_readlane_b32 s41, v252, 17
	v_readlane_b32 s42, v252, 18
	v_readlane_b32 s43, v252, 19
	v_readlane_b32 s44, v252, 20
	v_readlane_b32 s45, v252, 21
	v_readlane_b32 s46, v252, 22
	v_readlane_b32 s47, v252, 23
	v_readlane_b32 s48, v252, 24
	v_readlane_b32 s49, v252, 25
	s_branch .LBB0_450
